# mLSTM scan hand-scheduled: batched LDS reads for stage 1 MFMAs and K^T operand, DPP gate prefix sum, merged commit writes
# speedup vs baseline: 1.1092x; 1.0856x over previous
.LBB0_803:
	s_or_b64 exec, exec, s[18:19]
	s_mul_hi_i32 s18, s21, 0x2080000
	s_mul_i32 s21, s21, 0x2080000
	s_add_u32 s19, s12, s21
	s_addc_u32 s18, s13, s18
	s_lshl_b32 s21, s22, 1
	v_and_b32_e32 v84, 15, v110
	s_add_u32 s14, s14, s21
	v_lshlrev_b32_e32 v85, 1, v110
	s_addc_u32 s15, s15, 0
	s_lshl_b32 s20, s20, 4
	v_lshl_or_b32 v93, v111, 4, v84
	v_lshrrev_b32_e32 v86, 4, v82
	v_and_b32_e32 v88, 0xffffff80, v85
	s_add_u32 s62, s14, s20
	v_lshlrev_b32_e32 v85, 2, v82
	v_and_b32_e32 v82, 48, v82
	v_mul_lo_u32 v94, v93, s51
	s_addc_u32 s63, s15, 0
	v_readlane_b32 s24, v255, 4
	s_add_i32 s23, 0, 0x10a00
	v_add3_u32 v137, 0, v94, v82
	v_lshlrev_b32_e32 v94, 2, v93
	v_lshlrev_b32_e32 v141, 9, v86
	v_lshlrev_b32_e32 v89, 1, v84
	v_add_u32_e32 v132, s24, v85
	v_add_u32_e32 v133, s88, v85
	v_add_u32_e32 v134, s23, v85
	v_mul_u32_u24_e32 v92, 0x210, v84
	v_mad_u32_u24 v85, v84, s51, 0
	v_lshlrev_b32_e32 v135, 3, v86
	v_add_u32_e32 v139, s23, v94
	v_add_u32_e32 v95, 0, v141
	s_movk_i32 s23, 0xfe10
	v_mul_i32_i24_e32 v84, 0xfffffe40, v84
	v_add_u32_e32 v136, v85, v82
	v_add_u32_e32 v142, v95, v94
	v_mad_i32_i24 v95, v86, s23, v95
	v_add3_u32 v143, v85, v84, v135
	s_add_i32 s23, 0, 0x10200
	v_and_b32_e32 v85, 7, v110
	s_add_i32 s22, 0, 0x10b80
	v_add_u32_e32 v144, s23, v94
	v_ashrrev_i32_e32 v84, 3, v110
	v_lshlrev_b32_e32 v94, 5, v85
	v_add_lshl_u32 v94, v94, v84, 2
	s_add_u32 s19, s19, s21
	v_add_u32_e32 v145, s23, v94
	v_add_u32_e32 v146, 0, v94
	v_lshlrev_b32_e32 v94, 2, v84
	s_addc_u32 s21, s18, 0
	v_lshlrev_b32_e32 v87, 2, v86
	v_add_u32_e32 v96, s23, v94
	v_add_u32_e32 v148, 0, v94
	v_add_u32_e32 v149, s24, v94
	v_sub_u32_e32 v94, 31, v84
	s_add_u32 s18, s19, s20
	v_cndmask_b32_e64 v150, v94, v84, s[4:5]
	s_addc_u32 s19, s21, 0
	v_lshlrev_b32_e32 v84, 1, v85
	v_mov_b32_e32 v85, v17
	v_add_u32_e32 v154, s88, v82
	v_or_b32_e32 v82, 16, v87
	v_lshl_add_u64 v[84:85], s[18:19], 0, v[84:85]
	s_mov_b64 s[18:19], 0x6aa8000
	v_cmp_le_i32_e64 s[36:37], v82, v93
	v_lshl_add_u32 v158, v82, 2, s88
	v_or_b32_e32 v82, 17, v87
	v_lshl_add_u64 v[106:107], v[84:85], 0, s[18:19]
	s_movk_i32 s18, 0x1070
	v_cmp_le_i32_e64 s[38:39], v82, v93
	v_lshl_add_u32 v159, v82, 2, s88
	v_or_b32_e32 v82, 18, v87
	s_waitcnt lgkmcnt(0)
	v_mad_u32_u24 v84, v86, s18, v95
	v_lshl_add_u32 v153, v83, 4, s22
	v_or_b32_e32 v83, 1, v87
	v_cmp_le_i32_e64 s[40:41], v82, v93
	v_lshl_add_u32 v160, v82, 2, s88
	v_or_b32_e32 v82, 19, v87
	v_add3_u32 v90, 0, v88, v89
	v_and_b32_e32 v91, 31, v110
	v_lshl_add_u32 v151, v86, 5, s88
	v_add3_u32 v152, v84, v88, v89
	v_lshl_add_u64 v[108:109], s[16:17], 0, v[16:17]
	v_mul_u32_u24_e32 v16, 0x840, v86
	v_mul_u32_u24_e32 v84, 0x210, v83
	v_or_b32_e32 v85, 2, v87
	v_or_b32_e32 v86, 3, v87
	v_cmp_le_i32_e64 s[42:43], v82, v93
	v_lshl_add_u32 v161, v82, 2, s88
	v_mov_b32_e32 v82, 0
	v_cmp_gt_u32_e64 s[12:13], 64, v110
	v_lshl_add_u32 v131, v91, 4, s22
	v_cmp_lt_i32_e64 s[14:15], 1, v111
	v_add_u32_e32 v138, 0xffffbe00, v137
	v_add_u32_e32 v140, 0xffffff80, v139
	v_add_u32_e32 v147, 0x400, v96
	s_mov_b32 s52, 0
	v_cmp_eq_u32_e64 s[16:17], 0, v91
	v_cmp_gt_u32_e64 s[18:19], 2, v91
	v_cmp_gt_u32_e64 s[20:21], 4, v91
	v_cmp_gt_u32_e64 s[22:23], 8, v91
	v_cmp_gt_u32_e64 s[24:25], 16, v91
	v_cmp_le_i32_e64 s[26:27], v87, v93
	v_cmp_lt_i32_e64 s[28:29], v87, v93
	v_lshl_add_u32 v155, v83, 2, s88
	v_cmp_le_i32_e64 s[30:31], v85, v93
	v_lshl_add_u32 v156, v85, 2, s88
	v_cmp_le_i32_e64 s[34:35], v86, v93
	v_lshl_add_u32 v157, v86, 2, s88
	v_lshlrev_b32_e32 v162, 7, v83
	v_lshlrev_b32_e32 v163, 7, v85
	v_lshlrev_b32_e32 v164, 7, v86
	v_add_u32_e32 v165, v90, v16
	v_add_u32_e32 v166, v90, v84
	v_add_u32_e32 v167, v95, v92
	s_mov_b32 s77, 0
	v_mov_b32_e32 v83, v82
	v_mov_b32_e32 v84, v82
	v_mov_b32_e32 v85, v82
	v_mov_b32_e32 v86, v82
	v_mov_b32_e32 v87, v82
	v_mov_b32_e32 v88, v82
	v_mov_b32_e32 v89, v82
	v_mov_b32_e32 v90, v82
	v_mov_b32_e32 v91, v82
	v_mov_b32_e32 v92, v82
	v_mov_b32_e32 v93, v82
	v_mov_b32_e32 v94, v82
	v_mov_b32_e32 v95, v82
	v_mov_b32_e32 v96, v82
	v_mov_b32_e32 v97, v82
	s_barrier
	v_cndmask_b32_e64 v155, 0, v228, s[8:9]
	v_cndmask_b32_e64 v156, 0, v228, s[8:9]
	v_cndmask_b32_e64 v157, 0, v228, s[8:9]
	v_cndmask_b32_e64 v158, 0, v228, s[8:9]
	v_cndmask_b32_e64 v159, 0, v228, s[8:9]
	v_cndmask_b32_e64 v160, 0, v228, s[8:9]
	v_cndmask_b32_e64 v161, 0, v228, s[8:9]
	v_cndmask_b32_e64 v177, 0, v228, s[8:9]
	v_add_u32_e32 v155, v155, v122
	v_add_u32_e32 v156, v156, v123
	v_add_u32_e32 v157, v157, v124
	v_add_u32_e32 v158, v158, v125
	v_add_u32_e32 v159, v159, v126
	v_add_u32_e32 v160, v160, v127
	v_add_u32_e32 v161, v161, v128
	v_add_u32_e32 v177, v177, v129
	s_branch .LBB0_806

.LBB0_810:
	s_and_saveexec_b64 s[44:45], s[12:13]
	s_cbranch_execz .LBB0_813
	ds_read_b128 v[98:101], v131
	s_waitcnt lgkmcnt(0)
	v_mov_b32_e32 v16, v98
	s_nop 1
	v_add_f32_dpp v16, v16, v16 row_shr:1 row_mask:0xf bank_mask:0xf bound_ctrl:1
	s_nop 1
	v_add_f32_dpp v16, v16, v16 row_shr:2 row_mask:0xf bank_mask:0xf bound_ctrl:1
	s_nop 1
	v_add_f32_dpp v16, v16, v16 row_shr:4 row_mask:0xf bank_mask:0xf bound_ctrl:1
	s_nop 1
	v_add_f32_dpp v16, v16, v16 row_shr:8 row_mask:0xf bank_mask:0xf bound_ctrl:1
	s_nop 1
	v_add_f32_dpp v16, v16, v16 row_bcast:15 row_mask:0xa bank_mask:0xf
	s_and_b64 exec, exec, s[6:7]
	s_cbranch_execz .LBB0_813
	v_sub_f32_e32 v98, v99, v16
	ds_write_b32 v134, v16
	ds_write_b32 v133, v98
	ds_write_b32 v132, v100
.LBB0_813:
	s_or_b64 exec, exec, s[44:45]
	v_cvt_pk_bf16_f32 v16, v94, v17
	ds_write_b16 v165, v16 offset:55552
	v_cvt_pk_bf16_f32 v16, v95, v17
	ds_write_b16 v166, v16 offset:55552
	v_cvt_pk_bf16_f32 v16, v96, v17
	ds_write_b16 v166, v16 offset:56080
	v_cvt_pk_bf16_f32 v16, v97, v17
	ds_write_b16 v166, v16 offset:56608
	v_cvt_pk_bf16_f32 v16, v90, v17
	ds_write_b16 v165, v16 offset:55584
	v_cvt_pk_bf16_f32 v16, v91, v17
	ds_write_b16 v166, v16 offset:55584
	v_cvt_pk_bf16_f32 v16, v92, v17
	ds_write_b16 v166, v16 offset:56112
	v_cvt_pk_bf16_f32 v16, v93, v17
	ds_write_b16 v166, v16 offset:56640
	v_cvt_pk_bf16_f32 v16, v86, v17
	ds_write_b16 v165, v16 offset:55616
	v_cvt_pk_bf16_f32 v16, v87, v17
	ds_write_b16 v166, v16 offset:55616
	v_cvt_pk_bf16_f32 v16, v88, v17
	ds_write_b16 v166, v16 offset:56144
	v_cvt_pk_bf16_f32 v16, v89, v17
	ds_write_b16 v166, v16 offset:56672
	v_cvt_pk_bf16_f32 v16, v82, v17
	ds_write_b16 v165, v16 offset:55648
	v_cvt_pk_bf16_f32 v16, v83, v17
	ds_write_b16 v166, v16 offset:55648
	v_cvt_pk_bf16_f32 v16, v84, v17
	ds_write_b16 v166, v16 offset:56176
	v_cvt_pk_bf16_f32 v16, v85, v17
	ds_write_b16 v166, v16 offset:56704
	s_waitcnt lgkmcnt(0)
	v_add_u32_e32 v168, 0xf800, v142
	s_barrier
	s_and_saveexec_b64 s[44:45], s[14:15]
	s_xor_b64 s[44:45], exec, s[44:45]
	s_cbranch_execz .Lm1_w01
	ds_read_b32 v16, v140
	ds_read_b128 v[180:183], v136 offset:55552
	ds_read_b128 v[184:187], v138
	ds_read_b128 v[188:191], v136 offset:55616
	ds_read_b128 v[192:195], v138 offset:64
	ds_read_b128 v[196:199], v136 offset:55680
	ds_read_b128 v[200:203], v138 offset:128
	ds_read_b128 v[204:207], v136 offset:55744
	ds_read_b128 v[212:215], v138 offset:192
	ds_read_b128 v[216:219], v136 offset:55808
	ds_read_b128 v[220:223], v138 offset:256
	ds_read_b128 v[230:233], v136 offset:55872
	ds_read_b128 v[234:237], v138 offset:320
	ds_read_b128 v[244:247], v136 offset:55936
	ds_read_b128 v[248:251], v138 offset:384
	s_waitcnt lgkmcnt(12)
	v_mul_f32_e32 v16, 0x3fb8aa3b, v16
	v_mfma_f32_16x16x32_bf16 v[98:101], v[180:183], v[184:187], 0
	ds_read_b128 v[180:183], v136 offset:56000
	ds_read_b128 v[184:187], v138 offset:448
	v_exp_f32_e32 v16, v16
	s_waitcnt lgkmcnt(12)
	v_mfma_f32_16x16x32_bf16 v[98:101], v[188:191], v[192:195], v[98:101]
	s_waitcnt lgkmcnt(10)
	v_mfma_f32_16x16x32_bf16 v[98:101], v[196:199], v[200:203], v[98:101]
	s_waitcnt lgkmcnt(8)
	v_mfma_f32_16x16x32_bf16 v[98:101], v[204:207], v[212:215], v[98:101]
	s_waitcnt lgkmcnt(6)
	v_mfma_f32_16x16x32_bf16 v[98:101], v[216:219], v[220:223], v[98:101]
	s_waitcnt lgkmcnt(4)
	v_mfma_f32_16x16x32_bf16 v[98:101], v[230:233], v[234:237], v[98:101]
	s_waitcnt lgkmcnt(2)
	v_mfma_f32_16x16x32_bf16 v[98:101], v[244:247], v[248:251], v[98:101]
	s_waitcnt lgkmcnt(0)
	v_mfma_f32_16x16x32_bf16 v[98:101], v[180:183], v[184:187], v[98:101]
	s_nop 7
	v_mul_f32_e32 v98, v98, v16
	v_mul_f32_e32 v99, v99, v16
	v_mul_f32_e32 v100, v100, v16
	v_mul_f32_e32 v101, v101, v16
	ds_write2_b32 v168, v98, v99 offset0:96 offset1:128
	ds_write2_b32 v168, v100, v101 offset0:160 offset1:192
.Lm1_w01:
	s_andn2_saveexec_b64 s[44:45], s[44:45]
	s_cbranch_execz .LBB0_829
	ds_read_b128 v[180:183], v137
	ds_read_b128 v[184:187], v167 offset:16896
	ds_read_b128 v[188:191], v167 offset:25344
	ds_read_b128 v[192:195], v137 offset:64
	ds_read_b128 v[196:199], v167 offset:16960
	ds_read_b128 v[200:203], v167 offset:25408
	ds_read_b128 v[204:207], v137 offset:128
	ds_read_b128 v[212:215], v167 offset:17024
	ds_read_b128 v[216:219], v167 offset:25472
	ds_read_b128 v[220:223], v137 offset:192
	ds_read_b128 v[230:233], v167 offset:17088
	ds_read_b128 v[234:237], v167 offset:25536
	ds_read_b128 v[244:247], v137 offset:256
	ds_read_b128 v[248:251], v167 offset:17152
	ds_read_b128 v[172:175], v167 offset:25600
	s_waitcnt lgkmcnt(12)
	v_mfma_f32_16x16x32_bf16 v[102:105], v[184:187], v[180:183], 0
	v_mfma_f32_16x16x32_bf16 v[98:101], v[188:191], v[180:183], 0
	ds_read_b128 v[180:183], v137 offset:320
	ds_read_b128 v[184:187], v167 offset:17216
	ds_read_b128 v[188:191], v167 offset:25664
	s_waitcnt lgkmcnt(12)
	v_mfma_f32_16x16x32_bf16 v[102:105], v[196:199], v[192:195], v[102:105]
	v_mfma_f32_16x16x32_bf16 v[98:101], v[200:203], v[192:195], v[98:101]
	ds_read_b128 v[192:195], v137 offset:384
	ds_read_b128 v[196:199], v167 offset:17280
	ds_read_b128 v[200:203], v167 offset:25728
	s_waitcnt lgkmcnt(12)
	v_mfma_f32_16x16x32_bf16 v[102:105], v[212:215], v[204:207], v[102:105]
	v_mfma_f32_16x16x32_bf16 v[98:101], v[216:219], v[204:207], v[98:101]
	ds_read_b128 v[204:207], v137 offset:448
	ds_read_b128 v[212:215], v167 offset:17344
	ds_read_b128 v[216:219], v167 offset:25792
	s_waitcnt lgkmcnt(12)
	v_mfma_f32_16x16x32_bf16 v[102:105], v[230:233], v[220:223], v[102:105]
	v_mfma_f32_16x16x32_bf16 v[98:101], v[234:237], v[220:223], v[98:101]
	ds_read_b32 v16, v139
	ds_read_b128 v[220:223], v154
	ds_read_b128 v[230:233], v154 offset:64
	s_waitcnt lgkmcnt(12)
	v_mfma_f32_16x16x32_bf16 v[102:105], v[248:251], v[244:247], v[102:105]
	v_mfma_f32_16x16x32_bf16 v[98:101], v[172:175], v[244:247], v[98:101]
	v_add_u32_e32 v244, 0xd000, v143
	ds_read2_b64 v[234:237], v244 offset0:128 offset1:132
	s_waitcnt lgkmcnt(10)
	v_mfma_f32_16x16x32_bf16 v[102:105], v[184:187], v[180:183], v[102:105]
	v_mfma_f32_16x16x32_bf16 v[98:101], v[188:191], v[180:183], v[98:101]
	s_waitcnt lgkmcnt(7)
	v_mfma_f32_16x16x32_bf16 v[102:105], v[196:199], v[192:195], v[102:105]
	v_mfma_f32_16x16x32_bf16 v[98:101], v[200:203], v[192:195], v[98:101]
	s_waitcnt lgkmcnt(4)
	v_mfma_f32_16x16x32_bf16 v[102:105], v[212:215], v[204:207], v[102:105]
	v_mfma_f32_16x16x32_bf16 v[98:101], v[216:219], v[204:207], v[98:101]
	s_waitcnt lgkmcnt(1)
	v_add_f32_e32 v220, v16, v220
	v_add_f32_e32 v221, v16, v221
	v_add_f32_e32 v222, v16, v222
	v_add_f32_e32 v223, v16, v223
	v_add_f32_e32 v230, v16, v230
	v_add_f32_e32 v231, v16, v231
	v_add_f32_e32 v232, v16, v232
	v_add_f32_e32 v233, v16, v233
	v_mul_f32_e32 v220, 0x3fb8aa3b, v220
	v_mul_f32_e32 v221, 0x3fb8aa3b, v221
	v_mul_f32_e32 v222, 0x3fb8aa3b, v222
	v_mul_f32_e32 v223, 0x3fb8aa3b, v223
	v_mul_f32_e32 v230, 0x3fb8aa3b, v230
	v_mul_f32_e32 v231, 0x3fb8aa3b, v231
	v_mul_f32_e32 v232, 0x3fb8aa3b, v232
	v_mul_f32_e32 v233, 0x3fb8aa3b, v233
	v_exp_f32_e32 v220, v220
	v_exp_f32_e32 v221, v221
	v_exp_f32_e32 v222, v222
	v_exp_f32_e32 v223, v223
	v_exp_f32_e32 v230, v230
	v_exp_f32_e32 v231, v231
	v_exp_f32_e32 v232, v232
	v_exp_f32_e32 v233, v233
	v_mul_f32_e32 v220, v102, v220
	v_mul_f32_e32 v221, v103, v221
	v_mul_f32_e32 v222, v104, v222
	v_mul_f32_e32 v223, v105, v223
	v_mul_f32_e32 v230, v98, v230
	v_mul_f32_e32 v231, v99, v231
	v_mul_f32_e32 v232, v100, v232
	v_mul_f32_e32 v233, v101, v233
	v_cndmask_b32_e64 v220, 0, v220, s[26:27]
	v_cndmask_b32_e64 v221, 0, v221, s[28:29]
	v_cndmask_b32_e64 v222, 0, v222, s[30:31]
	v_cndmask_b32_e64 v223, 0, v223, s[34:35]
	v_cndmask_b32_e64 v230, 0, v230, s[36:37]
	v_cndmask_b32_e64 v231, 0, v231, s[38:39]
	v_cndmask_b32_e64 v232, 0, v232, s[40:41]
	v_cndmask_b32_e64 v233, 0, v233, s[42:43]
	v_cvt_pk_bf16_f32 v100, v220, v221
	v_cvt_pk_bf16_f32 v101, v222, v223
	v_cvt_pk_bf16_f32 v102, v230, v231
	v_cvt_pk_bf16_f32 v103, v232, v233
	v_add_u32_e32 v245, v144, v141
	v_add_u32_e32 v246, v144, v162
	v_add_u32_e32 v247, v144, v163
	v_add_u32_e32 v248, v144, v164
	s_waitcnt lgkmcnt(0)
	v_mfma_f32_16x16x32_bf16 v[98:101], v[234:237], v[100:103], 0
	s_nop 7
	ds_write_b32 v245, v98
	ds_write_b32 v246, v99
	ds_write_b32 v247, v100
	ds_write_b32 v248, v101
.LBB0_829:
	s_or_b64 exec, exec, s[44:45]
	v_sub_co_u32_e64 v16, s[44:45], s77, 8
	s_waitcnt lgkmcnt(14)
	v_mov_b32_e32 v98, s77
	s_and_b64 s[74:75], s[44:45], exec
	v_cndmask_b32_e64 v16, v16, v98, s[44:45]
	s_cselect_b32 s78, 7, 0x1ff
	v_sub_u32_e32 v98, s78, v16
	v_cndmask_b32_e64 v16, v98, v16, s[4:5]
	s_waitcnt lgkmcnt(0)
	s_barrier
	ds_read_b32 v98, v145
	ds_read_b32 v99, v146 offset:64000
	s_cselect_b32 s74, 0x4000, 0
	v_add_u32_e32 v169, s74, v150
	v_add_u32_e32 v170, v143, v135
	s_waitcnt lgkmcnt(0)
	v_add_f32_e32 v98, v98, v99
	ds_read_b32 v99, v147
	ds_read_b32 v100, v148 offset:65024
	s_waitcnt lgkmcnt(0)
	v_add_f32_e32 v99, v99, v100
	ds_read_b32 v100, v149
	s_waitcnt lgkmcnt(0)
	v_max_f32_e32 v100, v100, v100
	v_max_f32_e64 v99, |v99|, v100
	v_rcp_f32_e32 v99, v99
	s_nop 0
	v_mul_f32_e32 v98, v98, v99
	v_cvt_pk_bf16_f32 v100, v98, v17
	v_lshl_add_u32 v98, v16, 5, v169
	v_ashrrev_i32_e32 v99, 31, v98
	v_lshlrev_b64 v[98:99], 11, v[98:99]
	v_lshl_add_u64 v[98:99], v[106:107], 0, v[98:99]
	v_mov_b32_e32 v16, s89
	global_store_short v[98:99], v100, off
	ds_read_b32 v171, v16
	ds_read_b128 v[98:101], v170 offset:54272
	ds_read_b128 v[102:105], v151
	ds_read_b128 v[172:175], v151 offset:16
	ds_read_u16 v180, v152 offset:16896
	ds_read_u16 v196, v152 offset:17424
	ds_read_u16 v181, v152 offset:17952
	ds_read_u16 v197, v152 offset:18480
	ds_read_u16 v182, v152 offset:19008
	ds_read_u16 v198, v152 offset:19536
	ds_read_u16 v183, v152 offset:20064
	ds_read_u16 v199, v152 offset:20592
	s_waitcnt lgkmcnt(8)
	v_lshlrev_b32_e32 v176, 16, v98
	v_add_f32_e32 v103, v171, v103
	v_mul_f32_e32 v103, 0x3fb8aa3b, v103
	v_exp_f32_e32 v103, v103
	v_add_f32_e32 v102, v171, v102
	v_mul_f32_e32 v102, 0x3fb8aa3b, v102
	v_and_b32_e32 v98, 0xffff0000, v98
	v_exp_f32_e32 v102, v102
	v_mul_f32_e32 v98, v103, v98
	v_add_f32_e32 v103, v171, v104
	v_mul_f32_e32 v103, 0x3fb8aa3b, v103
	v_exp_f32_e32 v103, v103
	v_mul_f32_e32 v102, v102, v176
	v_cvt_pk_bf16_f32 v98, v102, v98
	v_lshlrev_b32_e32 v102, 16, v99
	v_mul_f32_e32 v102, v103, v102
	v_add_f32_e32 v103, v171, v105
	v_mul_f32_e32 v103, 0x3fb8aa3b, v103
	s_waitcnt lgkmcnt(0)
	v_lshl_or_b32 v180, v196, 16, v180
	v_lshl_or_b32 v181, v197, 16, v181
	v_lshl_or_b32 v182, v198, 16, v182
	v_lshl_or_b32 v183, v199, 16, v183
	ds_read_u16 v184, v152 offset:16928
	ds_read_u16 v200, v152 offset:17456
	ds_read_u16 v185, v152 offset:17984
	ds_read_u16 v201, v152 offset:18512
	ds_read_u16 v186, v152 offset:19040
	ds_read_u16 v202, v152 offset:19568
	ds_read_u16 v187, v152 offset:20096
	ds_read_u16 v203, v152 offset:20624
	v_exp_f32_e32 v103, v103
	v_and_b32_e32 v99, 0xffff0000, v99
	v_mul_f32_e32 v16, 0x3fb8aa3b, v171
	v_exp_f32_e32 v16, v16
	v_mul_f32_e32 v99, v103, v99
	v_add_f32_e32 v103, v171, v172
	v_mul_f32_e32 v103, 0x3fb8aa3b, v103
	v_exp_f32_e32 v103, v103
	v_cvt_pk_bf16_f32 v99, v102, v99
	v_lshlrev_b32_e32 v102, 16, v100
	v_and_b32_e32 v100, 0xffff0000, v100
	v_mul_f32_e32 v102, v103, v102
	v_add_f32_e32 v103, v171, v173
	v_mul_f32_e32 v103, 0x3fb8aa3b, v103
	v_exp_f32_e32 v103, v103
	v_pk_mul_f32 v[96:97], v[96:97], v[16:17] op_sel_hi:[1,0]
	v_pk_mul_f32 v[94:95], v[94:95], v[16:17] op_sel_hi:[1,0]
	v_pk_mul_f32 v[92:93], v[92:93], v[16:17] op_sel_hi:[1,0]
	s_waitcnt lgkmcnt(0)
	v_lshl_or_b32 v184, v200, 16, v184
	v_lshl_or_b32 v185, v201, 16, v185
	v_lshl_or_b32 v186, v202, 16, v186
	v_lshl_or_b32 v187, v203, 16, v187
	ds_read_u16 v188, v152 offset:16960
	ds_read_u16 v204, v152 offset:17488
	ds_read_u16 v189, v152 offset:18016
	ds_read_u16 v205, v152 offset:18544
	ds_read_u16 v190, v152 offset:19072
	ds_read_u16 v206, v152 offset:19600
	ds_read_u16 v191, v152 offset:20128
	ds_read_u16 v207, v152 offset:20656
	v_mul_f32_e32 v100, v103, v100
	v_add_f32_e32 v103, v171, v174
	v_mul_f32_e32 v103, 0x3fb8aa3b, v103
	v_exp_f32_e32 v103, v103
	v_cvt_pk_bf16_f32 v100, v102, v100
	v_lshlrev_b32_e32 v102, 16, v101
	v_and_b32_e32 v101, 0xffff0000, v101
	v_mul_f32_e32 v102, v103, v102
	v_add_f32_e32 v103, v171, v175
	v_mul_f32_e32 v103, 0x3fb8aa3b, v103
	v_exp_f32_e32 v103, v103
	v_pk_mul_f32 v[90:91], v[90:91], v[16:17] op_sel_hi:[1,0]
	v_pk_mul_f32 v[88:89], v[88:89], v[16:17] op_sel_hi:[1,0]
	v_pk_mul_f32 v[86:87], v[86:87], v[16:17] op_sel_hi:[1,0]
	v_mul_f32_e32 v101, v103, v101
	v_cvt_pk_bf16_f32 v101, v102, v101
	v_pk_mul_f32 v[84:85], v[84:85], v[16:17] op_sel_hi:[1,0]
	v_pk_mul_f32 v[82:83], v[82:83], v[16:17] op_sel_hi:[1,0]
	s_waitcnt lgkmcnt(0)
	v_lshl_or_b32 v188, v204, 16, v188
	v_lshl_or_b32 v189, v205, 16, v189
	v_lshl_or_b32 v190, v206, 16, v190
	v_lshl_or_b32 v191, v207, 16, v191
	ds_read_u16 v192, v152 offset:16992
	ds_read_u16 v212, v152 offset:17520
	ds_read_u16 v193, v152 offset:18048
	ds_read_u16 v213, v152 offset:18576
	ds_read_u16 v194, v152 offset:19104
	ds_read_u16 v214, v152 offset:19632
	ds_read_u16 v195, v152 offset:20160
	ds_read_u16 v215, v152 offset:20688
	s_waitcnt lgkmcnt(0)
	v_lshl_or_b32 v192, v212, 16, v192
	v_lshl_or_b32 v193, v213, 16, v193
	v_lshl_or_b32 v194, v214, 16, v194
	v_lshl_or_b32 v195, v215, 16, v195
	s_barrier
	s_nop 1
	v_mfma_f32_16x16x32_bf16 v[94:97], v[98:101], v[180:183], v[94:97]
	v_mfma_f32_16x16x32_bf16 v[90:93], v[98:101], v[184:187], v[90:93]
	v_mfma_f32_16x16x32_bf16 v[86:89], v[98:101], v[188:191], v[86:89]
	v_mfma_f32_16x16x32_bf16 v[82:85], v[98:101], v[192:195], v[82:85]
	s_waitcnt vmcnt(8)
	ds_write_b128 v155, v[46:49]
	s_waitcnt vmcnt(7)
	ds_write_b128 v156, v[50:53]
	s_waitcnt vmcnt(6)
	ds_write_b128 v157, v[54:57]
	s_waitcnt vmcnt(5)
	ds_write_b128 v158, v[58:61]
	s_waitcnt vmcnt(4)
	ds_write_b128 v159, v[66:69]
	s_waitcnt vmcnt(3)
	ds_write_b128 v160, v[70:73]
	s_waitcnt vmcnt(2)
	ds_write_b128 v161, v[74:77]
	s_waitcnt vmcnt(1)
	ds_write_b128 v177, v[78:81]
	s_and_saveexec_b64 s[74:75], s[10:11]
	s_cbranch_execz .LBB0_847

.LBB0_851:
	s_and_saveexec_b64 s[58:59], s[12:13]
	s_cbranch_execz .LBB0_854
	ds_read_b128 v[98:101], v131
	s_waitcnt lgkmcnt(0)
	v_mov_b32_e32 v16, v98
	s_nop 1
	v_add_f32_dpp v16, v16, v16 row_shr:1 row_mask:0xf bank_mask:0xf bound_ctrl:1
	s_nop 1
	v_add_f32_dpp v16, v16, v16 row_shr:2 row_mask:0xf bank_mask:0xf bound_ctrl:1
	s_nop 1
	v_add_f32_dpp v16, v16, v16 row_shr:4 row_mask:0xf bank_mask:0xf bound_ctrl:1
	s_nop 1
	v_add_f32_dpp v16, v16, v16 row_shr:8 row_mask:0xf bank_mask:0xf bound_ctrl:1
	s_nop 1
	v_add_f32_dpp v16, v16, v16 row_bcast:15 row_mask:0xa bank_mask:0xf
	s_and_b64 exec, exec, s[6:7]
	s_cbranch_execz .LBB0_854
	v_sub_f32_e32 v98, v99, v16
	ds_write_b32 v134, v16
	ds_write_b32 v133, v98
	ds_write_b32 v132, v100
.LBB0_854:
	s_or_b64 exec, exec, s[58:59]
	v_cvt_pk_bf16_f32 v16, v94, v17
	ds_write_b16 v165, v16 offset:55552
	v_cvt_pk_bf16_f32 v16, v95, v17
	ds_write_b16 v166, v16 offset:55552
	v_cvt_pk_bf16_f32 v16, v96, v17
	ds_write_b16 v166, v16 offset:56080
	v_cvt_pk_bf16_f32 v16, v97, v17
	ds_write_b16 v166, v16 offset:56608
	v_cvt_pk_bf16_f32 v16, v90, v17
	ds_write_b16 v165, v16 offset:55584
	v_cvt_pk_bf16_f32 v16, v91, v17
	ds_write_b16 v166, v16 offset:55584
	v_cvt_pk_bf16_f32 v16, v92, v17
	ds_write_b16 v166, v16 offset:56112
	v_cvt_pk_bf16_f32 v16, v93, v17
	ds_write_b16 v166, v16 offset:56640
	v_cvt_pk_bf16_f32 v16, v86, v17
	ds_write_b16 v165, v16 offset:55616
	v_cvt_pk_bf16_f32 v16, v87, v17
	ds_write_b16 v166, v16 offset:55616
	v_cvt_pk_bf16_f32 v16, v88, v17
	ds_write_b16 v166, v16 offset:56144
	v_cvt_pk_bf16_f32 v16, v89, v17
	ds_write_b16 v166, v16 offset:56672
	v_cvt_pk_bf16_f32 v16, v82, v17
	ds_write_b16 v165, v16 offset:55648
	v_cvt_pk_bf16_f32 v16, v83, v17
	ds_write_b16 v166, v16 offset:55648
	v_cvt_pk_bf16_f32 v16, v84, v17
	ds_write_b16 v166, v16 offset:56176
	v_cvt_pk_bf16_f32 v16, v85, v17
	ds_write_b16 v166, v16 offset:56704
	s_waitcnt lgkmcnt(0)
	s_barrier
	s_and_saveexec_b64 s[58:59], s[14:15]
	s_xor_b64 s[58:59], exec, s[58:59]
	s_cbranch_execz .Lm2_w01
	ds_read_b32 v16, v140
	ds_read_b128 v[180:183], v136 offset:55552
	ds_read_b128 v[184:187], v138
	ds_read_b128 v[188:191], v136 offset:55616
	ds_read_b128 v[192:195], v138 offset:64
	ds_read_b128 v[196:199], v136 offset:55680
	ds_read_b128 v[200:203], v138 offset:128
	ds_read_b128 v[204:207], v136 offset:55744
	ds_read_b128 v[212:215], v138 offset:192
	ds_read_b128 v[216:219], v136 offset:55808
	ds_read_b128 v[220:223], v138 offset:256
	ds_read_b128 v[230:233], v136 offset:55872
	ds_read_b128 v[234:237], v138 offset:320
	ds_read_b128 v[244:247], v136 offset:55936
	ds_read_b128 v[248:251], v138 offset:384
	s_waitcnt lgkmcnt(12)
	v_mul_f32_e32 v16, 0x3fb8aa3b, v16
	v_mfma_f32_16x16x32_bf16 v[98:101], v[180:183], v[184:187], 0
	ds_read_b128 v[180:183], v136 offset:56000
	ds_read_b128 v[184:187], v138 offset:448
	v_exp_f32_e32 v16, v16
	s_waitcnt lgkmcnt(12)
	v_mfma_f32_16x16x32_bf16 v[98:101], v[188:191], v[192:195], v[98:101]
	s_waitcnt lgkmcnt(10)
	v_mfma_f32_16x16x32_bf16 v[98:101], v[196:199], v[200:203], v[98:101]
	s_waitcnt lgkmcnt(8)
	v_mfma_f32_16x16x32_bf16 v[98:101], v[204:207], v[212:215], v[98:101]
	s_waitcnt lgkmcnt(6)
	v_mfma_f32_16x16x32_bf16 v[98:101], v[216:219], v[220:223], v[98:101]
	s_waitcnt lgkmcnt(4)
	v_mfma_f32_16x16x32_bf16 v[98:101], v[230:233], v[234:237], v[98:101]
	s_waitcnt lgkmcnt(2)
	v_mfma_f32_16x16x32_bf16 v[98:101], v[244:247], v[248:251], v[98:101]
	s_waitcnt lgkmcnt(0)
	v_mfma_f32_16x16x32_bf16 v[98:101], v[180:183], v[184:187], v[98:101]
	s_nop 7
	v_mul_f32_e32 v98, v98, v16
	v_mul_f32_e32 v99, v99, v16
	v_mul_f32_e32 v100, v100, v16
	v_mul_f32_e32 v101, v101, v16
	ds_write2_b32 v168, v98, v99 offset0:96 offset1:128
	ds_write2_b32 v168, v100, v101 offset0:160 offset1:192
.Lm2_w01:
	s_andn2_saveexec_b64 s[58:59], s[58:59]
	s_cbranch_execz .LBB0_870
	ds_read_b128 v[180:183], v137
	ds_read_b128 v[184:187], v167 offset:16896
	ds_read_b128 v[188:191], v167 offset:25344
	ds_read_b128 v[192:195], v137 offset:64
	ds_read_b128 v[196:199], v167 offset:16960
	ds_read_b128 v[200:203], v167 offset:25408
	ds_read_b128 v[204:207], v137 offset:128
	ds_read_b128 v[212:215], v167 offset:17024
	ds_read_b128 v[216:219], v167 offset:25472
	ds_read_b128 v[220:223], v137 offset:192
	ds_read_b128 v[230:233], v167 offset:17088
	ds_read_b128 v[234:237], v167 offset:25536
	ds_read_b128 v[244:247], v137 offset:256
	ds_read_b128 v[248:251], v167 offset:17152
	ds_read_b128 v[172:175], v167 offset:25600
	s_waitcnt lgkmcnt(12)
	v_mfma_f32_16x16x32_bf16 v[102:105], v[184:187], v[180:183], 0
	v_mfma_f32_16x16x32_bf16 v[98:101], v[188:191], v[180:183], 0
	ds_read_b128 v[180:183], v137 offset:320
	ds_read_b128 v[184:187], v167 offset:17216
	ds_read_b128 v[188:191], v167 offset:25664
	s_waitcnt lgkmcnt(12)
	v_mfma_f32_16x16x32_bf16 v[102:105], v[196:199], v[192:195], v[102:105]
	v_mfma_f32_16x16x32_bf16 v[98:101], v[200:203], v[192:195], v[98:101]
	ds_read_b128 v[192:195], v137 offset:384
	ds_read_b128 v[196:199], v167 offset:17280
	ds_read_b128 v[200:203], v167 offset:25728
	s_waitcnt lgkmcnt(12)
	v_mfma_f32_16x16x32_bf16 v[102:105], v[212:215], v[204:207], v[102:105]
	v_mfma_f32_16x16x32_bf16 v[98:101], v[216:219], v[204:207], v[98:101]
	ds_read_b128 v[204:207], v137 offset:448
	ds_read_b128 v[212:215], v167 offset:17344
	ds_read_b128 v[216:219], v167 offset:25792
	s_waitcnt lgkmcnt(12)
	v_mfma_f32_16x16x32_bf16 v[102:105], v[230:233], v[220:223], v[102:105]
	v_mfma_f32_16x16x32_bf16 v[98:101], v[234:237], v[220:223], v[98:101]
	ds_read_b32 v16, v139
	ds_read_b128 v[220:223], v154
	ds_read_b128 v[230:233], v154 offset:64
	s_waitcnt lgkmcnt(12)
	v_mfma_f32_16x16x32_bf16 v[102:105], v[248:251], v[244:247], v[102:105]
	v_mfma_f32_16x16x32_bf16 v[98:101], v[172:175], v[244:247], v[98:101]
	v_add_u32_e32 v244, 0xd000, v143
	ds_read2_b64 v[234:237], v244 offset0:128 offset1:132
	s_waitcnt lgkmcnt(10)
	v_mfma_f32_16x16x32_bf16 v[102:105], v[184:187], v[180:183], v[102:105]
	v_mfma_f32_16x16x32_bf16 v[98:101], v[188:191], v[180:183], v[98:101]
	s_waitcnt lgkmcnt(7)
	v_mfma_f32_16x16x32_bf16 v[102:105], v[196:199], v[192:195], v[102:105]
	v_mfma_f32_16x16x32_bf16 v[98:101], v[200:203], v[192:195], v[98:101]
	s_waitcnt lgkmcnt(4)
	v_mfma_f32_16x16x32_bf16 v[102:105], v[212:215], v[204:207], v[102:105]
	v_mfma_f32_16x16x32_bf16 v[98:101], v[216:219], v[204:207], v[98:101]
	s_waitcnt lgkmcnt(1)
	v_add_f32_e32 v220, v16, v220
	v_add_f32_e32 v221, v16, v221
	v_add_f32_e32 v222, v16, v222
	v_add_f32_e32 v223, v16, v223
	v_add_f32_e32 v230, v16, v230
	v_add_f32_e32 v231, v16, v231
	v_add_f32_e32 v232, v16, v232
	v_add_f32_e32 v233, v16, v233
	v_mul_f32_e32 v220, 0x3fb8aa3b, v220
	v_mul_f32_e32 v221, 0x3fb8aa3b, v221
	v_mul_f32_e32 v222, 0x3fb8aa3b, v222
	v_mul_f32_e32 v223, 0x3fb8aa3b, v223
	v_mul_f32_e32 v230, 0x3fb8aa3b, v230
	v_mul_f32_e32 v231, 0x3fb8aa3b, v231
	v_mul_f32_e32 v232, 0x3fb8aa3b, v232
	v_mul_f32_e32 v233, 0x3fb8aa3b, v233
	v_exp_f32_e32 v220, v220
	v_exp_f32_e32 v221, v221
	v_exp_f32_e32 v222, v222
	v_exp_f32_e32 v223, v223
	v_exp_f32_e32 v230, v230
	v_exp_f32_e32 v231, v231
	v_exp_f32_e32 v232, v232
	v_exp_f32_e32 v233, v233
	v_mul_f32_e32 v220, v102, v220
	v_mul_f32_e32 v221, v103, v221
	v_mul_f32_e32 v222, v104, v222
	v_mul_f32_e32 v223, v105, v223
	v_mul_f32_e32 v230, v98, v230
	v_mul_f32_e32 v231, v99, v231
	v_mul_f32_e32 v232, v100, v232
	v_mul_f32_e32 v233, v101, v233
	v_cndmask_b32_e64 v220, 0, v220, s[26:27]
	v_cndmask_b32_e64 v221, 0, v221, s[28:29]
	v_cndmask_b32_e64 v222, 0, v222, s[30:31]
	v_cndmask_b32_e64 v223, 0, v223, s[34:35]
	v_cndmask_b32_e64 v230, 0, v230, s[36:37]
	v_cndmask_b32_e64 v231, 0, v231, s[38:39]
	v_cndmask_b32_e64 v232, 0, v232, s[40:41]
	v_cndmask_b32_e64 v233, 0, v233, s[42:43]
	v_cvt_pk_bf16_f32 v100, v220, v221
	v_cvt_pk_bf16_f32 v101, v222, v223
	v_cvt_pk_bf16_f32 v102, v230, v231
	v_cvt_pk_bf16_f32 v103, v232, v233
	v_add_u32_e32 v245, v144, v141
	v_add_u32_e32 v246, v144, v162
	v_add_u32_e32 v247, v144, v163
	v_add_u32_e32 v248, v144, v164
	s_waitcnt lgkmcnt(0)
	v_mfma_f32_16x16x32_bf16 v[98:101], v[234:237], v[100:103], 0
	s_nop 7
	ds_write_b32 v245, v98
	ds_write_b32 v246, v99
	ds_write_b32 v247, v100
	ds_write_b32 v248, v101
.LBB0_870:
	s_or_b64 exec, exec, s[58:59]
	s_waitcnt lgkmcnt(0)
	s_barrier
	ds_read_b32 v16, v145
	s_waitcnt lgkmcnt(14)
	ds_read_b32 v98, v146 offset:64000
	s_add_i32 s58, s77, 1
	s_add_i32 s59, s77, -7
	s_and_b64 s[44:45], s[44:45], exec
	s_cselect_b32 s59, s58, s59
	s_waitcnt lgkmcnt(0)
	v_add_f32_e32 v16, v16, v98
	ds_read_b32 v98, v147
	ds_read_b32 v99, v148 offset:65024
	s_sub_i32 s74, s78, s59
	s_and_b64 s[44:45], s[4:5], exec
	s_cselect_b32 s44, s59, s74
	s_cmpk_gt_u32 s58, 0x206
	s_waitcnt lgkmcnt(0)
	v_add_f32_e32 v98, v98, v99
	ds_read_b32 v99, v149
	s_waitcnt lgkmcnt(0)
	v_max_f32_e32 v99, v99, v99
	v_max_f32_e64 v98, |v98|, v99
	v_rcp_f32_e32 v98, v98
	s_nop 0
	v_mul_f32_e32 v16, v16, v98
	v_lshl_add_u32 v98, s44, 5, v169
	v_ashrrev_i32_e32 v99, 31, v98
	v_lshlrev_b64 v[98:99], 11, v[98:99]
	v_cvt_pk_bf16_f32 v16, v16, v17
	v_lshl_add_u64 v[98:99], v[106:107], 0, v[98:99]
	global_store_short v[98:99], v16, off
	v_mov_b32_e32 v16, s89
	ds_read_b32 v172, v16
	ds_read_b128 v[98:101], v170 offset:54272
	ds_read_b128 v[102:105], v151
	ds_read_b128 v[168:171], v151 offset:16
	ds_read_u16 v180, v152 offset:16896
	ds_read_u16 v196, v152 offset:17424
	ds_read_u16 v181, v152 offset:17952
	ds_read_u16 v197, v152 offset:18480
	ds_read_u16 v182, v152 offset:19008
	ds_read_u16 v198, v152 offset:19536
	ds_read_u16 v183, v152 offset:20064
	ds_read_u16 v199, v152 offset:20592
	s_waitcnt lgkmcnt(8)
	v_lshlrev_b32_e32 v173, 16, v98
	v_add_f32_e32 v103, v172, v103
	v_mul_f32_e32 v103, 0x3fb8aa3b, v103
	v_exp_f32_e32 v103, v103
	v_add_f32_e32 v102, v172, v102
	v_mul_f32_e32 v102, 0x3fb8aa3b, v102
	v_and_b32_e32 v98, 0xffff0000, v98
	v_exp_f32_e32 v102, v102
	v_mul_f32_e32 v98, v103, v98
	v_add_f32_e32 v103, v172, v104
	v_mul_f32_e32 v103, 0x3fb8aa3b, v103
	v_exp_f32_e32 v103, v103
	v_mul_f32_e32 v102, v102, v173
	v_cvt_pk_bf16_f32 v98, v102, v98
	v_lshlrev_b32_e32 v102, 16, v99
	v_mul_f32_e32 v102, v103, v102
	v_add_f32_e32 v103, v172, v105
	v_mul_f32_e32 v103, 0x3fb8aa3b, v103
	s_waitcnt lgkmcnt(0)
	v_lshl_or_b32 v180, v196, 16, v180
	v_lshl_or_b32 v181, v197, 16, v181
	v_lshl_or_b32 v182, v198, 16, v182
	v_lshl_or_b32 v183, v199, 16, v183
	ds_read_u16 v184, v152 offset:16928
	ds_read_u16 v200, v152 offset:17456
	ds_read_u16 v185, v152 offset:17984
	ds_read_u16 v201, v152 offset:18512
	ds_read_u16 v186, v152 offset:19040
	ds_read_u16 v202, v152 offset:19568
	ds_read_u16 v187, v152 offset:20096
	ds_read_u16 v203, v152 offset:20624
	v_exp_f32_e32 v103, v103
	v_and_b32_e32 v99, 0xffff0000, v99
	v_mul_f32_e32 v16, 0x3fb8aa3b, v172
	v_exp_f32_e32 v16, v16
	v_mul_f32_e32 v99, v103, v99
	v_add_f32_e32 v103, v172, v168
	v_mul_f32_e32 v103, 0x3fb8aa3b, v103
	v_exp_f32_e32 v103, v103
	v_cvt_pk_bf16_f32 v99, v102, v99
	v_lshlrev_b32_e32 v102, 16, v100
	v_and_b32_e32 v100, 0xffff0000, v100
	v_mul_f32_e32 v102, v103, v102
	v_add_f32_e32 v103, v172, v169
	v_mul_f32_e32 v103, 0x3fb8aa3b, v103
	v_exp_f32_e32 v103, v103
	v_pk_mul_f32 v[96:97], v[96:97], v[16:17] op_sel_hi:[1,0]
	v_pk_mul_f32 v[94:95], v[94:95], v[16:17] op_sel_hi:[1,0]
	v_pk_mul_f32 v[92:93], v[92:93], v[16:17] op_sel_hi:[1,0]
	s_waitcnt lgkmcnt(0)
	v_lshl_or_b32 v184, v200, 16, v184
	v_lshl_or_b32 v185, v201, 16, v185
	v_lshl_or_b32 v186, v202, 16, v186
	v_lshl_or_b32 v187, v203, 16, v187
	ds_read_u16 v188, v152 offset:16960
	ds_read_u16 v204, v152 offset:17488
	ds_read_u16 v189, v152 offset:18016
	ds_read_u16 v205, v152 offset:18544
	ds_read_u16 v190, v152 offset:19072
	ds_read_u16 v206, v152 offset:19600
	ds_read_u16 v191, v152 offset:20128
	ds_read_u16 v207, v152 offset:20656
	v_mul_f32_e32 v100, v103, v100
	v_add_f32_e32 v103, v172, v170
	v_mul_f32_e32 v103, 0x3fb8aa3b, v103
	v_exp_f32_e32 v103, v103
	v_cvt_pk_bf16_f32 v100, v102, v100
	v_lshlrev_b32_e32 v102, 16, v101
	v_and_b32_e32 v101, 0xffff0000, v101
	v_mul_f32_e32 v102, v103, v102
	v_add_f32_e32 v103, v172, v171
	v_mul_f32_e32 v103, 0x3fb8aa3b, v103
	v_exp_f32_e32 v103, v103
	v_pk_mul_f32 v[90:91], v[90:91], v[16:17] op_sel_hi:[1,0]
	v_pk_mul_f32 v[88:89], v[88:89], v[16:17] op_sel_hi:[1,0]
	v_pk_mul_f32 v[86:87], v[86:87], v[16:17] op_sel_hi:[1,0]
	v_mul_f32_e32 v101, v103, v101
	v_cvt_pk_bf16_f32 v101, v102, v101
	v_pk_mul_f32 v[84:85], v[84:85], v[16:17] op_sel_hi:[1,0]
	v_pk_mul_f32 v[82:83], v[82:83], v[16:17] op_sel_hi:[1,0]
	s_waitcnt lgkmcnt(0)
	v_lshl_or_b32 v188, v204, 16, v188
	v_lshl_or_b32 v189, v205, 16, v189
	v_lshl_or_b32 v190, v206, 16, v190
	v_lshl_or_b32 v191, v207, 16, v191
	ds_read_u16 v192, v152 offset:16992
	ds_read_u16 v212, v152 offset:17520
	ds_read_u16 v193, v152 offset:18048
	ds_read_u16 v213, v152 offset:18576
	ds_read_u16 v194, v152 offset:19104
	ds_read_u16 v214, v152 offset:19632
	ds_read_u16 v195, v152 offset:20160
	ds_read_u16 v215, v152 offset:20688
	s_waitcnt lgkmcnt(0)
	v_lshl_or_b32 v192, v212, 16, v192
	v_lshl_or_b32 v193, v213, 16, v193
	v_lshl_or_b32 v194, v214, 16, v194
	v_lshl_or_b32 v195, v215, 16, v195
	s_barrier
	s_nop 1
	v_mfma_f32_16x16x32_bf16 v[94:97], v[98:101], v[180:183], v[94:97]
	v_mfma_f32_16x16x32_bf16 v[90:93], v[98:101], v[184:187], v[90:93]
	v_mfma_f32_16x16x32_bf16 v[86:89], v[98:101], v[188:191], v[86:89]
	v_mfma_f32_16x16x32_bf16 v[82:85], v[98:101], v[192:195], v[82:85]
	s_cbranch_scc1 .LBB0_805
	s_waitcnt vmcnt(9)
	ds_write_b128 v155, v[0:3]
	s_waitcnt vmcnt(8)
	ds_write_b128 v156, v[4:7]
	s_waitcnt vmcnt(7)
	ds_write_b128 v157, v[8:11]
	s_waitcnt vmcnt(6)
	ds_write_b128 v158, v[12:15]
	s_waitcnt vmcnt(5)
	ds_write_b128 v159, v[22:25]
	s_waitcnt vmcnt(4)
	ds_write_b128 v160, v[30:33]
	s_waitcnt vmcnt(3)
	ds_write_b128 v161, v[38:41]
	s_waitcnt vmcnt(2)
	ds_write_b128 v177, v[42:45]
	s_and_saveexec_b64 s[44:45], s[10:11]
	s_cbranch_execz .LBB0_804
	s_branch .LBB0_928
